# grid barrier: early L2 write-back by the arriver twelve places before the last of its XCC (variant of the four-places version)
# baseline (speedup 1.0000x reference)
; DEV unsigned xb_add(unsigned* p, unsigned v) { return __hip_atomic_fetch_add(p, v, __ATOMIC_RELAXED, __HIP_MEMORY_SCOPE_AGENT); }
; DEV void xcd_barrier(const XcdBarrier& b) {
;     ...
;         const unsigned old = xb_add(&bar[XB_XSUB(b.x)], 1u);
;         const unsigned gen = old / nloc;
;         if (old + 1u == (gen + 1u) * nloc) {
;             __builtin_amdgcn_fence(__ATOMIC_RELEASE, "agent");
;             asm volatile("s_waitcnt vmcnt(0)" ::: "memory");
;             const unsigned og = xb_add(&bar[XB_TOP], 1u);
;             const unsigned tg = og / nx;
;             if (og + 1u == (tg + 1u) * nx) xb_add(&bar[XB_TOPGEN], 1u);
.LBB0_134:
	s_lshl_b32 s6, s3, 8
	v_mov_b32_e32 v2, 0x20008
	s_add_u32 s6, s28, s6
	s_addc_u32 s7, s29, 0
	ds_read_b32 v2, v2
	v_mov_b32_e32 v4, 0x1000
	v_mov_b32_e32 v5, 1
	global_atomic_add v4, v4, v5, s[6:7] offset:1024 sc0
	s_waitcnt vmcnt(0) lgkmcnt(0)
	buffer_inv sc1
	v_readfirstlane_b32 s8, v4
	v_readfirstlane_b32 s9, v3
	v_readfirstlane_b32 s10, v2
	v_readfirstlane_b32 s11, v1
	s_add_i32 s12, s10, 1
	v_mov_b32_e32 v6, 0x20008
	v_mov_b32_e32 v5, s12
	ds_write_b32 v6, v5
	s_add_i32 s8, s8, 1
	s_mul_i32 s13, s12, s9
	s_sub_i32 s16, s13, 12
	s_cmp_lg_u32 s8, s16
	s_cbranch_scc1 .Lxb0_nopre
	buffer_wbl2 sc1
